# index xhalf merge: raw partial-sum registers swapped in place where dead (drops remaining copies at 6 sites)
# speedup vs baseline: 1.0048x; 1.0048x over previous
; DI float xhalf_sum(float v) { const auto r = __builtin_amdgcn_permlane32_swap(__float_as_uint(v), __float_as_uint(v), false, false); return __uint_as_float(r[0]) + __uint_as_float(r[1]); }
; DI void phase_index(const Params& p, unsigned char* lds) {
;     ...
;             for (int q = 0; q < 4; ++q) {
;                 float pr = 0.f;
; #pragma unroll
;                 for (int e = 0; e < 4; ++e) pr += wq[q][e] * fmaxf(s[4 * q + e], 0.f);
;                 tot[q] = xhalf_sum(pr);
;             }
;             const int key = k0 + 32 * kb + r32;
; #pragma unroll
;             for (int qq = 0; qq < 2; ++qq) {
;                 const float t_lo = tot[qq], t_hi = tot[2 + qq];
;                 const float sc = ((lane & 32) ? t_hi : t_lo) + 0.0f;
;                 const unsigned ub = __float_as_uint(sc);
;                 const unsigned uk = ub ^ ((unsigned)((int)ub >> 31) | 0x80000000u);
;                 const bool valid = DIAG ? (key <= tq0 + qq) : true;
;                 if (PASS == 0) {
;                     if (valid) { const unsigned a = (uk >> 21) & 0x7feu; atomicAdd((unsigned*)(lds + hbase0 + qq * 2048 + (a & ~3u)), 1u << ((a & 2u) << 3)); }
;                 } else if (PASS == 1) {
;                     if (valid && (int)(uk >> 22) == b1v[qq]) { const unsigned a = (uk >> 11) & 0x7feu; atomicAdd((unsigned*)(lds + hbase0 + qq * 2048 + (a & ~3u)), 1u << ((a & 2u) << 3)); }
;                 } else if (PASS == 3) {
;                     if (valid) {
;                         const int k10 = (int)(uk >> 22), d = k10 - b1v[qq];
;                         if (k10 > hiv[qq]) cntA[qq] += 1;
;                         else if (d >= 0) {
;                             const unsigned bin = ((unsigned)d << sbv[qq]) | ((uk >> (22 - sbv[qq])) & ((1u << sbv[qq]) - 1u));
;                             const unsigned a = bin << 1;
;                             atomicAdd((unsigned*)(lds + hbase0 + qq * 2048 + (a & ~3u)), 1u << ((a & 2u) << 3));
;                         }
;                     }
.LBB0_2669:
	s_nop 0
	v_permlane32_swap_b32_e32 v173, v174
	v_add_f32_e32 v167, v173, v174
	v_add_f32_e32 v167, 0, v167
	v_ashrrev_i32_e32 v178, 31, v167
	v_bitop3_b32 v167, v178, v167, s82 bitop3:0x36
	v_lshrrev_b32_e32 v178, 22, v167
	v_permlane32_swap_b32_e32 v170, v172
	v_cmp_le_i32_e32 vcc, v178, v101
	s_and_saveexec_b64 s[30:31], vcc
	s_xor_b64 s[30:31], exec, s[30:31]
	s_cbranch_execz .LBB0_2673
	v_sub_u32_e32 v178, v178, v100
	v_cmp_lt_i32_e32 vcc, -1, v178
	s_and_saveexec_b64 s[38:39], vcc
	s_cbranch_execz .LBB0_2672
	v_lshrrev_b32_e32 v167, v113, v167
	v_and_b32_e32 v167, v167, v114
	v_lshl_or_b32 v167, v178, v111, v167
	v_lshlrev_b32_e32 v178, 1, v167
	v_and_b32_e32 v178, -4, v178
	v_lshlrev_b32_e32 v167, 4, v167
	v_add_u32_e32 v178, v123, v178
	v_lshlrev_b32_e64 v167, v167, 1
	ds_add_u32 v178, v167

; DI void phase_index(const Params& p, unsigned char* lds) {
;     ...
;                 } else if (PASS == 3) {
;                     if (valid) {
;                         const int k10 = (int)(uk >> 22), d = k10 - b1v[qq];
;                         if (k10 > hiv[qq]) cntA[qq] += 1;
;                         else if (d >= 0) {
;                             const unsigned bin = ((unsigned)d << sbv[qq]) | ((uk >> (22 - sbv[qq])) & ((1u << sbv[qq]) - 1u));
;                             const unsigned a = bin << 1;
;                             atomicAdd((unsigned*)(lds + hbase0 + qq * 2048 + (a & ~3u)), 1u << ((a & 2u) << 3));
;                         }
;                     }
.LBB0_2673:
	s_or_saveexec_b64 s[30:31], s[30:31]
	v_mov_b32_e32 v167, v165
	s_xor_b64 exec, exec, s[30:31]
	v_add_u32_e32 v167, 1, v165
	s_or_b64 exec, exec, s[30:31]
	v_add_f32_e32 v169, v170, v172
	v_add_f32_e32 v169, 0, v169
	v_ashrrev_i32_e32 v175, 31, v169
	v_bitop3_b32 v169, v175, v169, s82 bitop3:0x36
	v_lshrrev_b32_e32 v175, 22, v169
	v_cmp_le_i32_e32 vcc, v175, v103
	s_and_saveexec_b64 s[30:31], vcc
	s_xor_b64 s[30:31], exec, s[30:31]
	s_cbranch_execz .LBB0_2679
	v_sub_u32_e32 v175, v175, v102
	v_cmp_lt_i32_e32 vcc, -1, v175
	s_and_saveexec_b64 s[38:39], vcc
	s_cbranch_execz .LBB0_2678
	v_lshrrev_b32_e32 v169, v115, v169
	v_and_b32_e32 v169, v169, v116
	v_lshl_or_b32 v169, v175, v112, v169
	v_lshlrev_b32_e32 v175, 1, v169
	v_and_b32_e32 v175, -4, v175
	v_lshlrev_b32_e32 v169, 4, v169
	v_add_u32_e32 v175, v123, v175
	v_lshlrev_b32_e64 v169, v169, 1
	ds_add_u32 v175, v169 offset:2048

; #define MFMA32(a, b, c) __builtin_amdgcn_mfma_f32_32x32x16_bf16((a), (b), (c), 0, 0, 0)
; DI float xhalf_sum(float v) { const auto r = __builtin_amdgcn_permlane32_swap(__float_as_uint(v), __float_as_uint(v), false, false); return __uint_as_float(r[0]) + __uint_as_float(r[1]); }
; DI void phase_index(const Params& p, unsigned char* lds) {
;     ...
;         auto mma = [&](f32x16& s, unsigned off) {
; #pragma unroll
;             for (int i = 0; i < 16; ++i) s[i] = 0.f;
; #pragma unroll
;             for (int ks = 0; ks < 4; ++ks) { const bf16x8 kf = *(const bf16x8*)(lds + off + ks * 32); s = MFMA32(qf[ks], kf, s); }
;         };
;         auto proc = [&](auto PASSC, auto DIAGC, const f32x16& s, int k0, int kb) {
;             constexpr int PASS = decltype(PASSC)::value; constexpr bool DIAG = decltype(DIAGC)::value != 0;
;             f32x4 tot;
; #pragma unroll
;             for (int q = 0; q < 4; ++q) {
;                 float pr = 0.f;
; #pragma unroll
;                 for (int e = 0; e < 4; ++e) pr += wq[q][e] * fmaxf(s[4 * q + e], 0.f);
;                 tot[q] = xhalf_sum(pr);
;             }
;             const int key = k0 + 32 * kb + r32;
; #pragma unroll
;             for (int qq = 0; qq < 2; ++qq) {
;                 const float t_lo = tot[qq], t_hi = tot[2 + qq];
;                 const float sc = ((lane & 32) ? t_hi : t_lo) + 0.0f;
;                 const unsigned ub = __float_as_uint(sc);
;                 const unsigned uk = ub ^ ((unsigned)((int)ub >> 31) | 0x80000000u);
;                 const bool valid = DIAG ? (key <= tq0 + qq) : true;
;                 if (PASS == 0) {
;                     if (valid) { const unsigned a = (uk >> 21) & 0x7feu; atomicAdd((unsigned*)(lds + hbase0 + qq * 2048 + (a & ~3u)), 1u << ((a & 2u) << 3)); }
;                 } else if (PASS == 1) {
;                     if (valid && (int)(uk >> 22) == b1v[qq]) { const unsigned a = (uk >> 11) & 0x7feu; atomicAdd((unsigned*)(lds + hbase0 + qq * 2048 + (a & ~3u)), 1u << ((a & 2u) << 3)); }
.LBB0_3242:
	v_add_u32_e32 v115, s50, v113
	v_add_u32_e32 v18, 0x11200, v115
	ds_read_b128 v[18:21], v18
	v_add_u32_e32 v22, 0x11220, v115
	ds_read_b128 v[162:165], v22
	v_add_u32_e32 v167, 0x11240, v115
	s_waitcnt lgkmcnt(1)
	v_mfma_f32_32x32x16_bf16 v[18:33], v[42:45], v[18:21], 0
	v_max_f32_e32 v116, 0, v2
	v_max_f32_e32 v170, v6, v6
	v_max_f32_e32 v173, 0, v3
	v_fma_f32 v117, v50, v116, 0
	v_max_f32_e32 v172, v7, v7
	s_waitcnt lgkmcnt(0)
	v_mfma_f32_32x32x16_bf16 v[18:33], v[34:37], v[162:165], v[18:33]
	ds_read_b128 v[162:165], v167
	v_max_f32_e32 v161, 0, v4
	v_fmac_f32_e32 v117, v51, v173
	v_fmac_f32_e32 v117, v52, v161
	v_max_f32_e32 v161, 0, v8
	s_waitcnt lgkmcnt(0)
	v_mfma_f32_32x32x16_bf16 v[18:33], v[38:41], v[162:165], v[18:33]
	v_max_f32_e32 v162, 0, v170
	v_max_f32_e32 v163, 0, v172
	v_fma_f32 v116, v54, v162, 0
	v_fmac_f32_e32 v116, v55, v163
	v_fmac_f32_e32 v116, v56, v161
	v_max_f32_e32 v161, 0, v9
	v_fmac_f32_e32 v116, v57, v161
	v_max_f32_e32 v161, 0, v10
	v_add_u32_e32 v168, 0x11260, v115
	v_fma_f32 v162, v58, v161, 0
	v_max_f32_e32 v174, 0, v5
	ds_read_b128 v[166:169], v168
	v_max_f32_e32 v161, 0, v11
	v_fmac_f32_e32 v162, v59, v161
	v_max_f32_e32 v161, 0, v12
	v_fmac_f32_e32 v162, v60, v161
	v_max_f32_e32 v161, 0, v13
	s_waitcnt lgkmcnt(0)
	v_mfma_f32_32x32x16_bf16 v[18:33], v[46:49], v[166:169], v[18:33]
	v_fmac_f32_e32 v162, v61, v161
	v_max_f32_e32 v161, 0, v14
	v_fma_f32 v161, v62, v161, 0
	v_max_f32_e32 v163, 0, v15
	v_fmac_f32_e32 v161, v63, v163
	v_max_f32_e32 v163, 0, v16
	s_cmp_lg_u32 s0, s51
	v_fmac_f32_e32 v161, v64, v163
	s_cselect_b64 s[30:31], -1, 0
	v_max_f32_e32 v163, 0, v17
	v_fmac_f32_e32 v117, v53, v174
	v_fmac_f32_e32 v161, v65, v163
	s_and_b64 vcc, exec, s[30:31]
	s_cbranch_vccz .LBB0_3246
	s_nop 0
	v_permlane32_swap_b32_e32 v117, v162
	v_add_f32_e32 v167, v117, v162
	v_add_f32_e32 v167, 0, v167
	v_ashrrev_i32_e32 v168, 31, v167
	v_bitop3_b32 v167, v168, v167, s82 bitop3:0x36
	v_lshrrev_b32_e32 v168, 22, v167
	v_permlane32_swap_b32_e32 v116, v161
	v_cmp_eq_u32_e32 vcc, v168, v108
	s_and_saveexec_b64 s[26:27], vcc
	s_cbranch_execz .LBB0_3245
	v_lshrrev_b32_e32 v168, 11, v167
	v_lshrrev_b32_e32 v167, 8, v167
	v_and_b32_e32 v168, 0x7fc, v168
	v_and_b32_e32 v167, 16, v167
	v_add_u32_e32 v168, v123, v168
	v_lshlrev_b32_e64 v167, v167, 1
	ds_add_u32 v168, v167
.LBB0_3245:
	s_or_b64 exec, exec, s[26:27]
	v_add_f32_e32 v163, v116, v161
	v_add_f32_e32 v163, 0, v163
	v_ashrrev_i32_e32 v164, 31, v163
	v_bitop3_b32 v163, v164, v163, s82 bitop3:0x36
	v_lshrrev_b32_e32 v164, 22, v163
	v_cmp_eq_u32_e64 s[26:27], v164, v109
	s_branch .LBB0_3251

; DI float xhalf_sum(float v) { const auto r = __builtin_amdgcn_permlane32_swap(__float_as_uint(v), __float_as_uint(v), false, false); return __uint_as_float(r[0]) + __uint_as_float(r[1]); }
; DI void phase_index(const Params& p, unsigned char* lds) {
;     ...
;             for (int q = 0; q < 4; ++q) {
;                 float pr = 0.f;
; #pragma unroll
;                 for (int e = 0; e < 4; ++e) pr += wq[q][e] * fmaxf(s[4 * q + e], 0.f);
;                 tot[q] = xhalf_sum(pr);
;             }
;             const int key = k0 + 32 * kb + r32;
; #pragma unroll
;             for (int qq = 0; qq < 2; ++qq) {
;                 const float t_lo = tot[qq], t_hi = tot[2 + qq];
;                 const float sc = ((lane & 32) ? t_hi : t_lo) + 0.0f;
;                 const unsigned ub = __float_as_uint(sc);
;                 const unsigned uk = ub ^ ((unsigned)((int)ub >> 31) | 0x80000000u);
;                 const bool valid = DIAG ? (key <= tq0 + qq) : true;
;                 if (PASS == 0) {
;                     if (valid) { const unsigned a = (uk >> 21) & 0x7feu; atomicAdd((unsigned*)(lds + hbase0 + qq * 2048 + (a & ~3u)), 1u << ((a & 2u) << 3)); }
;                 } else if (PASS == 1) {
;                     if (valid && (int)(uk >> 22) == b1v[qq]) { const unsigned a = (uk >> 11) & 0x7feu; atomicAdd((unsigned*)(lds + hbase0 + qq * 2048 + (a & ~3u)), 1u << ((a & 2u) << 3)); }
.LBB0_3254:
	v_max_f32_e32 v18, 0, v18
	v_fma_f32 v115, v50, v18, 0
	v_max_f32_e32 v18, 0, v19
	v_fmac_f32_e32 v115, v51, v18
	v_max_f32_e32 v18, 0, v20
	v_fmac_f32_e32 v115, v52, v18
	v_max_f32_e32 v18, 0, v21
	v_fmac_f32_e32 v115, v53, v18
	v_max_f32_e32 v18, 0, v22
	v_fma_f32 v18, v54, v18, 0
	v_max_f32_e32 v19, 0, v23
	v_fmac_f32_e32 v18, v55, v19
	v_max_f32_e32 v19, 0, v24
	v_fmac_f32_e32 v18, v56, v19
	v_max_f32_e32 v19, 0, v25
	v_fmac_f32_e32 v18, v57, v19
	v_max_f32_e32 v19, 0, v26
	v_fma_f32 v20, v58, v19, 0
	v_max_f32_e32 v19, 0, v27
	v_fmac_f32_e32 v20, v59, v19
	v_max_f32_e32 v19, 0, v28
	v_fmac_f32_e32 v20, v60, v19
	v_max_f32_e32 v19, 0, v29
	v_fmac_f32_e32 v20, v61, v19
	v_max_f32_e32 v19, 0, v30
	v_fma_f32 v19, v62, v19, 0
	v_max_f32_e32 v21, 0, v31
	v_fmac_f32_e32 v19, v63, v21
	v_max_f32_e32 v21, 0, v32
	v_fmac_f32_e32 v19, v64, v21
	v_max_f32_e32 v21, 0, v33
	v_fmac_f32_e32 v19, v65, v21
	s_and_b64 vcc, exec, s[30:31]
	s_cbranch_vccz .LBB0_3259
	s_nop 0
	v_permlane32_swap_b32_e32 v115, v20
	v_add_f32_e32 v25, v115, v20
	v_add_f32_e32 v25, 0, v25
	v_ashrrev_i32_e32 v26, 31, v25
	v_bitop3_b32 v25, v26, v25, s82 bitop3:0x36
	v_lshrrev_b32_e32 v26, 22, v25
	v_permlane32_swap_b32_e32 v18, v19
	v_cmp_eq_u32_e32 vcc, v26, v108
	s_and_saveexec_b64 s[26:27], vcc
	s_cbranch_execz .LBB0_3257
	v_lshrrev_b32_e32 v26, 11, v25
	v_lshrrev_b32_e32 v25, 8, v25
	v_and_b32_e32 v26, 0x7fc, v26
	v_and_b32_e32 v25, 16, v25
	v_add_u32_e32 v26, v123, v26
	v_lshlrev_b32_e64 v25, v25, 1
	ds_add_u32 v26, v25
.LBB0_3257:
	s_or_b64 exec, exec, s[26:27]
	v_add_f32_e32 v21, v18, v19
	v_add_f32_e32 v21, 0, v21
	v_ashrrev_i32_e32 v22, 31, v21
	v_bitop3_b32 v21, v22, v21, s82 bitop3:0x36
	v_lshrrev_b32_e32 v22, 22, v21
	v_cmp_eq_u32_e64 s[26:27], v22, v109
	s_branch .LBB0_3264
